# v45 + attention row sums via v_pk_add_f32 (5 instead of 8 instructions per 8 values) and s_nop after exp groups removed
# baseline (speedup 1.0000x reference)
.Latt_noload:
	ds_read_b128 v[66:69], v0 offset:0
	ds_read_b128 v[70:73], v0 offset:6656
	ds_read_b128 v[74:77], v0 offset:32
	ds_read_b128 v[78:81], v0 offset:6688
	ds_read_b128 v[212:215], v0 offset:64
	ds_read_b128 v[240:243], v0 offset:6720
	ds_read_b128 v[244:247], v0 offset:96
	s_waitcnt lgkmcnt(6)
	v_mfma_f32_32x32x16_bf16 v[114:129], v[66:69], v[154:157], v[82:97]
	ds_read_b128 v[248:251], v0 offset:6752
	s_waitcnt lgkmcnt(6)
	v_mfma_f32_32x32x16_bf16 v[98:113], v[70:73], v[154:157], v[82:97]
	ds_read_b128 v[66:69], v0 offset:128
	s_waitcnt lgkmcnt(6)
	v_mfma_f32_32x32x16_bf16 v[114:129], v[74:77], v[158:161], v[114:129]
	ds_read_b128 v[70:73], v0 offset:6784
	s_waitcnt lgkmcnt(6)
	v_mfma_f32_32x32x16_bf16 v[98:113], v[78:81], v[158:161], v[98:113]
	ds_read_b128 v[74:77], v0 offset:160
	s_waitcnt lgkmcnt(6)
	v_mfma_f32_32x32x16_bf16 v[114:129], v[212:215], v[162:165], v[114:129]
	ds_read_b128 v[78:81], v0 offset:6816
	s_waitcnt lgkmcnt(6)
	v_mfma_f32_32x32x16_bf16 v[98:113], v[240:243], v[162:165], v[98:113]
	ds_read_b128 v[212:215], v0 offset:13312
	s_waitcnt lgkmcnt(6)
	v_mfma_f32_32x32x16_bf16 v[114:129], v[244:247], v[166:169], v[114:129]
	ds_read_b128 v[240:243], v0 offset:19968
	s_waitcnt lgkmcnt(6)
	v_mfma_f32_32x32x16_bf16 v[98:113], v[248:251], v[166:169], v[98:113]
	ds_read_b128 v[244:247], v0 offset:13344
	s_waitcnt lgkmcnt(6)
	v_mfma_f32_32x32x16_bf16 v[114:129], v[66:69], v[170:173], v[114:129]
	ds_read_b128 v[248:251], v0 offset:20000
	s_waitcnt lgkmcnt(6)
	v_mfma_f32_32x32x16_bf16 v[98:113], v[70:73], v[170:173], v[98:113]
	ds_read_b128 v[66:69], v0 offset:13376
	s_waitcnt lgkmcnt(6)
	v_mfma_f32_32x32x16_bf16 v[114:129], v[74:77], v[174:177], v[114:129]
	ds_read_b128 v[70:73], v0 offset:20032
	s_waitcnt lgkmcnt(6)
	v_mfma_f32_32x32x16_bf16 v[98:113], v[78:81], v[174:177], v[98:113]
	ds_read_b128 v[74:77], v0 offset:13408
	s_waitcnt lgkmcnt(6)
	v_mfma_f32_32x32x16_bf16 v[2:17], v[212:215], v[154:157], v[82:97]
	ds_read_b128 v[78:81], v0 offset:20064
	s_waitcnt lgkmcnt(6)
	v_mfma_f32_32x32x16_bf16 v[18:33], v[240:243], v[154:157], v[82:97]
	ds_read_b128 v[212:215], v0 offset:13440
	s_waitcnt lgkmcnt(6)
	v_mfma_f32_32x32x16_bf16 v[2:17], v[244:247], v[158:161], v[2:17]
	ds_read_b128 v[240:243], v0 offset:20096
	s_waitcnt lgkmcnt(6)
	v_mfma_f32_32x32x16_bf16 v[18:33], v[248:251], v[158:161], v[18:33]
	ds_read_b128 v[244:247], v0 offset:13472
	s_waitcnt lgkmcnt(6)
	v_mfma_f32_32x32x16_bf16 v[2:17], v[66:69], v[162:165], v[2:17]
	ds_read_b128 v[248:251], v0 offset:20128
	s_waitcnt lgkmcnt(6)
	v_mfma_f32_32x32x16_bf16 v[18:33], v[70:73], v[162:165], v[18:33]
	ds_read_b64_tr_b16 v[216:217], v185 offset:53248
	ds_read_b64_tr_b16 v[218:219], v185 offset:53760
	s_waitcnt lgkmcnt(7)
	v_mfma_f32_32x32x16_bf16 v[2:17], v[74:77], v[166:169], v[2:17]
	ds_read_b64_tr_b16 v[220:221], v185 offset:57344
	ds_read_b64_tr_b16 v[222:223], v185 offset:57856
	s_waitcnt lgkmcnt(8)
	v_mfma_f32_32x32x16_bf16 v[18:33], v[78:81], v[166:169], v[18:33]
	ds_read_b64_tr_b16 v[224:225], v185 offset:54272
	ds_read_b64_tr_b16 v[226:227], v185 offset:54784
	s_waitcnt lgkmcnt(9)
	v_mfma_f32_32x32x16_bf16 v[2:17], v[212:215], v[170:173], v[2:17]
	ds_read_b64_tr_b16 v[228:229], v185 offset:58368
	ds_read_b64_tr_b16 v[230:231], v185 offset:58880
	s_waitcnt lgkmcnt(10)
	v_mfma_f32_32x32x16_bf16 v[18:33], v[240:243], v[170:173], v[18:33]
	ds_read_b64_tr_b16 v[232:233], v185 offset:55296
	ds_read_b64_tr_b16 v[234:235], v185 offset:55808
	s_waitcnt lgkmcnt(11)
	v_mfma_f32_32x32x16_bf16 v[2:17], v[244:247], v[174:177], v[2:17]
	ds_read_b64_tr_b16 v[236:237], v185 offset:59392
	ds_read_b64_tr_b16 v[238:239], v185 offset:59904
	s_waitcnt lgkmcnt(12)
	v_mfma_f32_32x32x16_bf16 v[18:33], v[248:251], v[174:177], v[18:33]
	v_exp_f32_e32 v114, v114
	v_exp_f32_e32 v115, v115
	v_exp_f32_e32 v116, v116
	v_exp_f32_e32 v117, v117
	v_exp_f32_e32 v118, v118
	v_exp_f32_e32 v119, v119
	v_exp_f32_e32 v120, v120
	v_exp_f32_e32 v121, v121
	v_cvt_pk_bf16_f32 v66, v114, v115
	v_cvt_pk_bf16_f32 v67, v116, v117
	v_cvt_pk_bf16_f32 v68, v118, v119
	v_cvt_pk_bf16_f32 v69, v120, v121
	v_pk_add_f32 v[178:179], v[114:115], v[116:117]
	v_pk_add_f32 v[180:181], v[118:119], v[120:121]
	v_pk_add_f32 v[178:179], v[178:179], v[180:181]
	v_add_f32_e32 v178, v178, v179
	v_add_f32_e32 v210, v210, v178
	ds_read_b64_tr_b16 v[240:241], v185 offset:56320
	ds_read_b64_tr_b16 v[242:243], v185 offset:56832
	ds_read_b64_tr_b16 v[244:245], v185 offset:60416
	s_waitcnt lgkmcnt(11)
	ds_read_b64_tr_b16 v[246:247], v185 offset:60928
	ds_read_b64_tr_b16 v[114:115], v184 offset:53248
	ds_read_b64_tr_b16 v[116:117], v184 offset:53760
	ds_read_b64_tr_b16 v[118:119], v184 offset:57344
	s_waitcnt lgkmcnt(11)
	ds_read_b64_tr_b16 v[120:121], v184 offset:57856
	v_exp_f32_e32 v122, v122
	v_exp_f32_e32 v123, v123
	v_exp_f32_e32 v124, v124
	v_mfma_f32_32x32x16_bf16 v[34:49], v[66:69], v[216:219], v[34:49]
	v_exp_f32_e32 v125, v125
	v_exp_f32_e32 v126, v126
	v_exp_f32_e32 v127, v127
	v_exp_f32_e32 v128, v128
	v_exp_f32_e32 v129, v129
	v_cvt_pk_bf16_f32 v70, v122, v123
	v_cvt_pk_bf16_f32 v71, v124, v125
	v_mfma_f32_32x32x16_bf16 v[50:65], v[66:69], v[220:223], v[50:65]
	v_cvt_pk_bf16_f32 v72, v126, v127
	v_cvt_pk_bf16_f32 v73, v128, v129
	v_pk_add_f32 v[178:179], v[122:123], v[124:125]
	v_pk_add_f32 v[180:181], v[126:127], v[128:129]
	v_pk_add_f32 v[178:179], v[178:179], v[180:181]
	v_add_f32_e32 v178, v178, v179
	v_add_f32_e32 v210, v210, v178
	ds_read_b64_tr_b16 v[122:123], v184 offset:54272
	ds_read_b64_tr_b16 v[124:125], v184 offset:54784
	ds_read_b64_tr_b16 v[126:127], v184 offset:58368
	s_waitcnt lgkmcnt(11)
	ds_read_b64_tr_b16 v[128:129], v184 offset:58880
	v_exp_f32_e32 v98, v98
	v_exp_f32_e32 v99, v99
	v_exp_f32_e32 v100, v100
	v_mfma_f32_32x32x16_bf16 v[34:49], v[70:73], v[224:227], v[34:49]
	v_exp_f32_e32 v101, v101
	v_exp_f32_e32 v102, v102
	v_exp_f32_e32 v103, v103
	v_exp_f32_e32 v104, v104
	v_exp_f32_e32 v105, v105
	v_cvt_pk_bf16_f32 v74, v98, v99
	v_cvt_pk_bf16_f32 v75, v100, v101
	v_mfma_f32_32x32x16_bf16 v[50:65], v[70:73], v[228:231], v[50:65]
	v_cvt_pk_bf16_f32 v76, v102, v103
	v_cvt_pk_bf16_f32 v77, v104, v105
	v_pk_add_f32 v[178:179], v[98:99], v[100:101]
	v_pk_add_f32 v[180:181], v[102:103], v[104:105]
	v_pk_add_f32 v[178:179], v[178:179], v[180:181]
	v_add_f32_e32 v178, v178, v179
	v_add_f32_e32 v210, v210, v178
	ds_read_b64_tr_b16 v[98:99], v184 offset:55296
	ds_read_b64_tr_b16 v[100:101], v184 offset:55808
	ds_read_b64_tr_b16 v[102:103], v184 offset:59392
	s_waitcnt lgkmcnt(11)
	ds_read_b64_tr_b16 v[104:105], v184 offset:59904
	v_exp_f32_e32 v106, v106
	v_exp_f32_e32 v107, v107
	v_exp_f32_e32 v108, v108
	v_mfma_f32_32x32x16_bf16 v[34:49], v[74:77], v[232:235], v[34:49]
	v_exp_f32_e32 v109, v109
	v_exp_f32_e32 v110, v110
	v_exp_f32_e32 v111, v111
	v_exp_f32_e32 v112, v112
	v_exp_f32_e32 v113, v113
	v_cvt_pk_bf16_f32 v78, v106, v107
	v_cvt_pk_bf16_f32 v79, v108, v109
	v_mfma_f32_32x32x16_bf16 v[50:65], v[74:77], v[236:239], v[50:65]
	v_cvt_pk_bf16_f32 v80, v110, v111
	v_cvt_pk_bf16_f32 v81, v112, v113
	v_pk_add_f32 v[178:179], v[106:107], v[108:109]
	v_pk_add_f32 v[180:181], v[110:111], v[112:113]
	v_pk_add_f32 v[178:179], v[178:179], v[180:181]
	v_add_f32_e32 v178, v178, v179
	v_add_f32_e32 v210, v210, v178
	ds_read_b64_tr_b16 v[106:107], v184 offset:56320
	ds_read_b64_tr_b16 v[108:109], v184 offset:56832
	ds_read_b64_tr_b16 v[110:111], v184 offset:60416
	s_waitcnt lgkmcnt(11)
	ds_read_b64_tr_b16 v[112:113], v184 offset:60928
	v_exp_f32_e32 v2, v2
	v_exp_f32_e32 v3, v3
	v_exp_f32_e32 v4, v4
	v_mfma_f32_32x32x16_bf16 v[34:49], v[78:81], v[240:243], v[34:49]
	v_exp_f32_e32 v5, v5
	v_exp_f32_e32 v6, v6
	v_exp_f32_e32 v7, v7
	v_exp_f32_e32 v8, v8
	v_exp_f32_e32 v9, v9
	v_cvt_pk_bf16_f32 v66, v2, v3
	v_cvt_pk_bf16_f32 v67, v4, v5
	v_mfma_f32_32x32x16_bf16 v[50:65], v[78:81], v[244:247], v[50:65]
	v_cvt_pk_bf16_f32 v68, v6, v7
	v_cvt_pk_bf16_f32 v69, v8, v9
	v_pk_add_f32 v[178:179], v[2:3], v[4:5]
	v_pk_add_f32 v[180:181], v[6:7], v[8:9]
	v_pk_add_f32 v[178:179], v[178:179], v[180:181]
	v_add_f32_e32 v178, v178, v179
	v_add_f32_e32 v210, v210, v178
	v_exp_f32_e32 v10, v10
	v_exp_f32_e32 v11, v11
	v_exp_f32_e32 v12, v12
	v_mfma_f32_32x32x16_bf16 v[34:49], v[66:69], v[114:117], v[34:49]
	v_exp_f32_e32 v13, v13
	v_exp_f32_e32 v14, v14
	v_exp_f32_e32 v15, v15
	v_exp_f32_e32 v16, v16
	v_exp_f32_e32 v17, v17
	v_cvt_pk_bf16_f32 v70, v10, v11
	v_cvt_pk_bf16_f32 v71, v12, v13
	v_mfma_f32_32x32x16_bf16 v[50:65], v[66:69], v[118:121], v[50:65]
	v_cvt_pk_bf16_f32 v72, v14, v15
	v_cvt_pk_bf16_f32 v73, v16, v17
	v_pk_add_f32 v[178:179], v[10:11], v[12:13]
	v_pk_add_f32 v[180:181], v[14:15], v[16:17]
	v_pk_add_f32 v[178:179], v[178:179], v[180:181]
	v_add_f32_e32 v178, v178, v179
	v_add_f32_e32 v210, v210, v178
	v_exp_f32_e32 v18, v18
	v_exp_f32_e32 v19, v19
	v_exp_f32_e32 v20, v20
	s_waitcnt lgkmcnt(10)
	v_mfma_f32_32x32x16_bf16 v[34:49], v[70:73], v[122:125], v[34:49]
	v_exp_f32_e32 v21, v21
	v_exp_f32_e32 v22, v22
	v_exp_f32_e32 v23, v23
	v_exp_f32_e32 v24, v24
	v_exp_f32_e32 v25, v25
	v_cvt_pk_bf16_f32 v74, v18, v19
	v_cvt_pk_bf16_f32 v75, v20, v21
	s_waitcnt lgkmcnt(8)
	v_mfma_f32_32x32x16_bf16 v[50:65], v[70:73], v[126:129], v[50:65]
	v_cvt_pk_bf16_f32 v76, v22, v23
	v_cvt_pk_bf16_f32 v77, v24, v25
	v_pk_add_f32 v[178:179], v[18:19], v[20:21]
	v_pk_add_f32 v[180:181], v[22:23], v[24:25]
	v_pk_add_f32 v[178:179], v[178:179], v[180:181]
	v_add_f32_e32 v178, v178, v179
	v_add_f32_e32 v210, v210, v178
	v_exp_f32_e32 v26, v26
	v_exp_f32_e32 v27, v27
	v_exp_f32_e32 v28, v28
	s_waitcnt lgkmcnt(6)
	v_mfma_f32_32x32x16_bf16 v[34:49], v[74:77], v[98:101], v[34:49]
	v_exp_f32_e32 v29, v29
	v_exp_f32_e32 v30, v30
	v_exp_f32_e32 v31, v31
	v_exp_f32_e32 v32, v32
	v_exp_f32_e32 v33, v33
	v_cvt_pk_bf16_f32 v78, v26, v27
	v_cvt_pk_bf16_f32 v79, v28, v29
	s_waitcnt lgkmcnt(4)
	v_mfma_f32_32x32x16_bf16 v[50:65], v[74:77], v[102:105], v[50:65]
	v_cvt_pk_bf16_f32 v80, v30, v31
	v_cvt_pk_bf16_f32 v81, v32, v33
	v_pk_add_f32 v[178:179], v[26:27], v[28:29]
	v_pk_add_f32 v[180:181], v[30:31], v[32:33]
	v_pk_add_f32 v[178:179], v[178:179], v[180:181]
	v_add_f32_e32 v178, v178, v179
	v_add_f32_e32 v210, v210, v178
	s_waitcnt lgkmcnt(2)
	v_mfma_f32_32x32x16_bf16 v[34:49], v[78:81], v[106:109], v[34:49]
	s_waitcnt lgkmcnt(0)
	v_mfma_f32_32x32x16_bf16 v[50:65], v[78:81], v[110:113], v[50:65]
	v_cmp_lt_f32_e32 vcc, 0x4b800000, v210
	s_cbranch_vccnz .Latt_rs
